# stack4 + G3 touch extended to the next unit's query and gate rows
# speedup vs baseline: 1.0062x; 1.0037x over previous
; __device__ __forceinline__ void g3_dma_unit(LAS unsigned char* lds, const bf16_t* P, const bf16_t* VAT, const bf16_t* DS, const float* BC, int uid, int wv, int lane) {
;     const int c = uid & 31, h = (uid >> 5) & 3, bl = uid >> 7;
;     const size_t row0 = (size_t)bl * SEQ + c * 64;
;     g3_dma_tile(lds + G3_KRAW, (const unsigned char*)(P + row0 * 2048 + 256 + h * 64), 4096, 8, 9, wv, lane);
; __device__ __forceinline__ void gla_g3(LAS unsigned char* lds, const bf16_t* P, const bf16_t* VAT, const bf16_t* DS, const float* BC, const float* gn, bf16_t* MIX) {
;     ...
;         const int c = uid & 31, h = (uid >> 5) & 3, bl = uid >> 7;
;         const size_t row0 = (size_t)bl * SEQ + c * 64, qrow = row0 + iq;
;         bf16x8 qraw[2]; f32x4 gvv[4]; u32x2 rvv[4];
; #pragma unroll
;         for (int s2 = 0; s2 < 2; ++s2) qraw[s2] = *(const bf16x8*)(P + qrow * 2048 + h * 64 + 32 * s2 + 8 * g);
; #pragma unroll
;         for (int mb = 0; mb < 4; ++mb) { const int cc = h * 128 + 16 * (4 * dvh + mb) + 4 * g; gvv[mb] = *(const f32x4*)(gn + cc); rvv[mb] = *(const u32x2*)(P + qrow * 2048 + 512 + cc); }
.Lg3_touch_c:
	global_load_lds_dword v[106:107], off
	s_cmp_gt_u32 s99, 5
	s_cbranch_scc1 .Lg3_touch_done
	s_cmp_eq_u32 s99, 1
	s_cbranch_scc1 .Lg3_touch_vt
	s_cmp_eq_u32 s99, 2
	s_cbranch_scc1 .Lg3_touch_vt
	s_bfe_u32 s101, s98, 0x20005
	s_cmp_lt_u32 s99, 4
	s_cbranch_scc0 .Lg3_touch_r
	s_lshl_b32 s101, s101, 7
	s_cmp_eq_u32 s99, 0
	s_cbranch_scc0 .Lg3_touch_p
	s_addk_i32 s101, 0x200
	s_branch .Lg3_touch_p
.Lg3_touch_r:
	s_lshl_b32 s101, s101, 8
	s_addk_i32 s101, 0x400
	s_cmp_eq_u32 s99, 5
	s_cbranch_scc0 .Lg3_touch_p
	s_addk_i32 s101, 0x80
.Lg3_touch_p:
	s_lshr_b32 s100, s98, 7
	s_lshl_b32 s100, s100, 11
	s_and_b32 s99, s98, 31
	s_lshl_b32 s99, s99, 6
	s_or_b32 s100, s100, s99
	v_add_u32_e32 v104, s100, v101
	v_lshlrev_b32_e32 v104, 12, v104
	v_add_u32_e32 v104, s101, v104
	v_lshl_add_u64 v[106:107], s[24:25], 0, v[104:105]
	global_load_lds_dword v[106:107], off
	s_branch .Lg3_touch_done
